# flash softmax: rescale running max only when it grows by more than 8 log2 units (exact math, fewer O rescales)
# speedup vs baseline: 1.0157x; 1.0047x over previous
.LBB0_986:
	v_max3_f32 v2, v96, s76, v97
	v_max3_f32 v2, v2, v98, v99
	v_max3_f32 v2, v2, v92, v93
	v_max3_f32 v2, v2, v94, v95
	v_max3_f32 v2, v2, v88, v89
	v_max3_f32 v2, v2, v90, v91
	v_max3_f32 v2, v2, v84, v85
	v_max3_f32 v2, v2, v86, v87
	v_mov_b32_e32 v3, v2
	s_nop 1
	v_permlane16_swap_b32 v3, v2
	s_waitcnt lgkmcnt(0)
	v_max_f32_e32 v3, v3, v3
	v_max_f32_e32 v2, v2, v3
	v_mov_b32_e32 v3, v2
	s_nop 1
	v_permlane32_swap_b32 v3, v2
	s_waitcnt lgkmcnt(0)
	v_max3_f32 v2, v124, v2, v3
	v_sub_f32_e32 v3, v2, v124
	v_cmp_lt_f32_e32 vcc, 0x40b17218, v3
	s_nop 1
	v_cndmask_b32_e32 v2, v124, v2, vcc
	v_mul_f32_e32 v3, 0xbfb8aa3b, v2
	v_fmamk_f32 v96, v96, 0x3fb8aa3b, v3
	v_fmamk_f32 v97, v97, 0x3fb8aa3b, v3
	v_fmamk_f32 v125, v93, 0x3fb8aa3b, v3
	v_exp_f32_e32 v93, v96
	v_fmamk_f32 v98, v98, 0x3fb8aa3b, v3
	v_fmamk_f32 v126, v94, 0x3fb8aa3b, v3
	v_exp_f32_e32 v94, v97
	v_fmamk_f32 v99, v99, 0x3fb8aa3b, v3
	v_exp_f32_e32 v96, v98
	v_fmamk_f32 v92, v92, 0x3fb8aa3b, v3
	v_exp_f32_e32 v97, v99
	v_exp_f32_e32 v98, v92
	v_add_f32_e32 v92, 0, v93
	v_exp_f32_e32 v99, v125
	v_add_f32_e32 v92, v94, v92
	v_add_f32_e32 v92, v96, v92
	v_exp_f32_e32 v125, v126
	v_fmamk_f32 v95, v95, 0x3fb8aa3b, v3
	v_add_f32_e32 v92, v97, v92
	v_exp_f32_e32 v95, v95
	v_fmamk_f32 v88, v88, 0x3fb8aa3b, v3
	v_add_f32_e32 v92, v98, v92
	v_exp_f32_e32 v88, v88
	v_fmamk_f32 v89, v89, 0x3fb8aa3b, v3
	v_add_f32_e32 v92, v99, v92
	v_exp_f32_e32 v89, v89
	v_fmamk_f32 v90, v90, 0x3fb8aa3b, v3
	v_add_f32_e32 v92, v125, v92
	v_exp_f32_e32 v90, v90
	v_fmamk_f32 v91, v91, 0x3fb8aa3b, v3
	v_add_f32_e32 v92, v95, v92
	v_exp_f32_e32 v91, v91
	v_add_f32_e32 v92, v88, v92
	v_add_f32_e32 v92, v89, v92
	v_add_f32_e32 v92, v90, v92
	v_fmamk_f32 v84, v84, 0x3fb8aa3b, v3
	v_add_f32_e32 v126, v91, v92
	v_exp_f32_e32 v92, v84
	v_fmamk_f32 v84, v85, 0x3fb8aa3b, v3
	v_exp_f32_e32 v85, v84
	v_fmamk_f32 v84, v86, 0x3fb8aa3b, v3
	v_exp_f32_e32 v86, v84
	v_fmac_f32_e32 v3, 0x3fb8aa3b, v87
	v_exp_f32_e32 v87, v3
	v_add_f32_e32 v3, v92, v126
	v_add_f32_e32 v3, v85, v3
	v_add_f32_e32 v3, v86, v3
	v_add_f32_e32 v3, v87, v3
	v_mov_b32_e32 v84, v3
	s_nop 1
	v_permlane16_swap_b32 v84, v3
	v_sub_f32_e32 v124, v124, v2
	v_mul_f32_e32 v124, 0x3fb8aa3b, v124
	v_exp_f32_e32 v124, v124
	s_waitcnt lgkmcnt(0)
	v_add_f32_e32 v126, v3, v84
	v_mov_b32_e32 v127, v126
	s_nop 1
	v_permlane32_swap_b32 v127, v126
	v_cmp_neq_f32_e32 vcc, 1.0, v124
	s_cbranch_vccz .LBB0_988
	ds_bpermute_b32 v128, v111, v124
	ds_bpermute_b32 v130, v117, v124
	ds_bpermute_b32 v131, v118, v124
	ds_bpermute_b32 v129, v116, v124
	s_waitcnt lgkmcnt(1)
	v_pk_mul_f32 v[62:63], v[62:63], v[130:131]
	s_waitcnt lgkmcnt(0)
	v_pk_mul_f32 v[60:61], v[60:61], v[128:129]
	v_pk_mul_f32 v[50:51], v[50:51], v[130:131]
	v_pk_mul_f32 v[48:49], v[48:49], v[128:129]
	v_pk_mul_f32 v[54:55], v[54:55], v[130:131]
	v_pk_mul_f32 v[52:53], v[52:53], v[128:129]
	v_pk_mul_f32 v[66:67], v[66:67], v[130:131]
	v_pk_mul_f32 v[64:65], v[64:65], v[128:129]
.LBB0_988:
	v_max3_f32 v3, v80, s76, v81
	v_max3_f32 v3, v3, v82, v83
	v_max3_f32 v3, v3, v76, v77
	v_max3_f32 v3, v3, v78, v79
	v_max3_f32 v3, v3, v72, v73
	v_max3_f32 v3, v3, v74, v75
	v_max3_f32 v3, v3, v68, v69
	v_max3_f32 v3, v3, v70, v71
	v_mov_b32_e32 v84, v3
	s_nop 1
	v_permlane16_swap_b32 v84, v3
	s_waitcnt lgkmcnt(0)
	v_max_f32_e32 v84, v84, v84
	v_max_f32_e32 v3, v3, v84
	v_mov_b32_e32 v84, v3
	s_nop 1
	v_permlane32_swap_b32 v84, v3
	s_waitcnt lgkmcnt(0)
	v_max3_f32 v84, v110, v3, v84
	v_sub_f32_e32 v3, v84, v110
	v_cmp_lt_f32_e32 vcc, 0x40b17218, v3
	s_nop 1
	v_cndmask_b32_e32 v84, v110, v84, vcc
	v_mul_f32_e32 v3, 0xbfb8aa3b, v84
	v_fmamk_f32 v80, v80, 0x3fb8aa3b, v3
	v_fmamk_f32 v81, v81, 0x3fb8aa3b, v3
	v_fmamk_f32 v128, v77, 0x3fb8aa3b, v3
	v_exp_f32_e32 v77, v80
	v_fmamk_f32 v82, v82, 0x3fb8aa3b, v3
	v_fmamk_f32 v129, v78, 0x3fb8aa3b, v3
	v_exp_f32_e32 v78, v81
	v_fmamk_f32 v83, v83, 0x3fb8aa3b, v3
	v_exp_f32_e32 v80, v82
	v_fmamk_f32 v76, v76, 0x3fb8aa3b, v3
	v_exp_f32_e32 v81, v83
	v_exp_f32_e32 v82, v76
	v_add_f32_e32 v76, 0, v77
	v_exp_f32_e32 v83, v128
	v_add_f32_e32 v76, v78, v76
	v_add_f32_e32 v76, v80, v76
	v_exp_f32_e32 v128, v129
	v_fmamk_f32 v79, v79, 0x3fb8aa3b, v3
	v_add_f32_e32 v76, v81, v76
	v_exp_f32_e32 v79, v79
	v_fmamk_f32 v72, v72, 0x3fb8aa3b, v3
	v_add_f32_e32 v76, v82, v76
	v_exp_f32_e32 v72, v72
	v_fmamk_f32 v73, v73, 0x3fb8aa3b, v3
	v_add_f32_e32 v76, v83, v76
	v_exp_f32_e32 v73, v73
	v_fmamk_f32 v74, v74, 0x3fb8aa3b, v3
	v_add_f32_e32 v76, v128, v76
	v_exp_f32_e32 v74, v74
	v_fmamk_f32 v75, v75, 0x3fb8aa3b, v3
	v_add_f32_e32 v76, v79, v76
	v_exp_f32_e32 v75, v75
	v_add_f32_e32 v76, v72, v76
	v_add_f32_e32 v76, v73, v76
	v_add_f32_e32 v76, v74, v76
	v_fmamk_f32 v68, v68, 0x3fb8aa3b, v3
	v_add_f32_e32 v129, v75, v76
	v_exp_f32_e32 v76, v68
	v_fmamk_f32 v68, v69, 0x3fb8aa3b, v3
	v_exp_f32_e32 v69, v68
	v_fmamk_f32 v68, v70, 0x3fb8aa3b, v3
	v_exp_f32_e32 v70, v68
	v_fmac_f32_e32 v3, 0x3fb8aa3b, v71
	v_exp_f32_e32 v71, v3
	v_add_f32_e32 v3, v76, v129
	v_add_f32_e32 v3, v69, v3
	v_add_f32_e32 v3, v70, v3
	v_add_f32_e32 v3, v71, v3
	v_mov_b32_e32 v129, v3
	s_nop 1
	v_permlane16_swap_b32 v129, v3
	v_sub_f32_e32 v68, v110, v84
	v_mul_f32_e32 v68, 0x3fb8aa3b, v68
	v_exp_f32_e32 v68, v68
	s_waitcnt lgkmcnt(0)
	v_add_f32_e32 v3, v3, v129
	v_mov_b32_e32 v110, v3
	s_nop 1
	v_permlane32_swap_b32 v110, v3
	v_cmp_neq_f32_e32 vcc, 1.0, v68
	s_cbranch_vccz .LBB0_990
	ds_bpermute_b32 v130, v111, v68
	ds_bpermute_b32 v132, v117, v68
	ds_bpermute_b32 v133, v118, v68
	ds_bpermute_b32 v131, v116, v68
	s_waitcnt lgkmcnt(1)
	v_pk_mul_f32 v[38:39], v[38:39], v[132:133]
	s_waitcnt lgkmcnt(0)
	v_pk_mul_f32 v[36:37], v[36:37], v[130:131]
	v_pk_mul_f32 v[42:43], v[42:43], v[132:133]
	v_pk_mul_f32 v[40:41], v[40:41], v[130:131]
	v_pk_mul_f32 v[46:47], v[46:47], v[132:133]
	v_pk_mul_f32 v[44:45], v[44:45], v[130:131]
	v_pk_mul_f32 v[58:59], v[58:59], v[132:133]
	v_pk_mul_f32 v[56:57], v[56:57], v[130:131]

.LBB0_1310:
	s_mov_b32 s10, s2
	s_add_i32 s10, s45, s10
	s_add_i32 s2, s2, 1
	s_add_i32 s10, s10, 33
	s_cmp_lt_u32 s2, s36
	s_cselect_b32 s11, s2, s10
	s_lshl_b32 s10, s11, 6
	s_cmp_lt_i32 s11, 32
	s_cselect_b32 s11, s8, s9
	s_add_i32 s11, s11, s10
	v_add_u32_e32 v2, s11, v150
	v_mad_i64_i32 v[2:3], s[20:21], v2, s6, v[130:131]
	s_barrier
	s_waitcnt vmcnt(5)
	ds_write_b128 v154, v[84:87]
	s_waitcnt vmcnt(4)
	ds_write_b128 v155, v[88:91]
	s_waitcnt vmcnt(3)
	ds_write_b128 v154, v[92:95] offset:9216
	s_waitcnt vmcnt(2)
	ds_write_b128 v155, v[96:99] offset:9216
	s_waitcnt vmcnt(1)
	ds_write_b128 v156, v[100:103] offset:9216
	s_waitcnt vmcnt(0)
	ds_write_b128 v157, v[104:107] offset:9216
	s_waitcnt lgkmcnt(0)
	s_barrier
	global_load_dwordx4 v[84:87], v[2:3], off
	v_add_u32_e32 v2, s11, v151
	s_ashr_i32 s11, s10, 31
	v_mad_i64_i32 v[2:3], s[20:21], v2, s6, v[130:131]
	s_lshl_b64 s[10:11], s[10:11], 1
	global_load_dwordx4 v[88:91], v[2:3], off
	v_lshl_add_u64 v[2:3], v[132:133], 0, s[10:11]
	global_load_dwordx4 v[92:95], v[2:3], off
	v_lshl_add_u64 v[2:3], v[134:135], 0, s[10:11]
	global_load_dwordx4 v[96:99], v[2:3], off
	v_lshl_add_u64 v[2:3], v[136:137], 0, s[10:11]
	global_load_dwordx4 v[100:103], v[2:3], off
	v_lshl_add_u64 v[2:3], v[138:139], 0, s[10:11]
	global_load_dwordx4 v[104:107], v[2:3], off
	v_add_u32_e32 v2, v152, v153
	ds_read_b128 v[108:111], v2
	ds_read_b128 v[116:119], v2 offset:64
	s_waitcnt lgkmcnt(1)
	v_mfma_f32_16x16x32_bf16 v[112:115], v[108:111], v[72:75], 0
	ds_read_b128 v[120:123], v2 offset:2368
	ds_read_b128 v[166:169], v2 offset:4672
	v_mov_b32_e32 v174, v159
	s_waitcnt lgkmcnt(2)
	v_mfma_f32_16x16x32_bf16 v[124:127], v[116:119], v[68:71], v[112:115]
	ds_read_b128 v[170:173], v2 offset:6976
	s_nop 1
	ds_read_b128 v[112:115], v2 offset:2304
	v_mfma_f32_16x16x32_bf16 v[108:111], v[108:111], v[76:79], 0
	s_nop 2
	v_max3_f32 v3, v124, s76, v125
	v_max3_f32 v3, v3, v126, v127
	v_mfma_f32_16x16x32_bf16 v[108:111], v[116:119], v[80:83], v[108:111]
	s_waitcnt lgkmcnt(0)
	v_mfma_f32_16x16x32_bf16 v[116:119], v[112:115], v[72:75], 0
	v_mfma_f32_16x16x32_bf16 v[162:165], v[120:123], v[68:71], v[116:119]
	v_mfma_f32_16x16x32_bf16 v[112:115], v[112:115], v[76:79], 0
	s_nop 5
	ds_read_b128 v[116:119], v2 offset:4608
	v_max3_f32 v3, v3, v162, v163
	v_max3_f32 v3, v3, v164, v165
	v_mfma_f32_16x16x32_bf16 v[112:115], v[120:123], v[80:83], v[112:115]
	s_waitcnt lgkmcnt(0)
	v_mfma_f32_16x16x32_bf16 v[120:123], v[116:119], v[72:75], 0
	v_mfma_f32_16x16x32_bf16 v[176:179], v[166:169], v[68:71], v[120:123]
	s_nop 6
	ds_read_b128 v[120:123], v2 offset:6912
	v_mfma_f32_16x16x32_bf16 v[116:119], v[116:119], v[76:79], 0
	v_max3_f32 v3, v3, v176, v177
	v_max3_f32 v3, v3, v178, v179
	v_mfma_f32_16x16x32_bf16 v[116:119], v[166:169], v[80:83], v[116:119]
	s_waitcnt lgkmcnt(0)
	v_mfma_f32_16x16x32_bf16 v[166:169], v[120:123], v[72:75], 0
	v_mfma_f32_16x16x32_bf16 v[180:183], v[170:173], v[68:71], v[166:169]
	v_mfma_f32_16x16x32_bf16 v[120:123], v[120:123], v[76:79], 0
	v_mfma_f32_16x16x32_bf16 v[120:123], v[170:173], v[80:83], v[120:123]
	s_nop 5
	v_max3_f32 v3, v3, v180, v181
	v_max3_f32 v3, v3, v182, v183
	v_mov_b32_e32 v159, v3
	s_nop 1
	v_permlane16_swap_b32 v159, v3
	s_waitcnt lgkmcnt(0)
	v_max_f32_e32 v159, v159, v159
	v_max_f32_e32 v3, v3, v159
	v_mov_b32_e32 v159, v3
	s_nop 1
	v_permlane32_swap_b32 v159, v3
	s_waitcnt lgkmcnt(0)
	v_max3_f32 v159, v174, v3, v159
	v_sub_f32_e32 v3, v159, v174
	v_cmp_lt_f32_e32 vcc, 0x40b17218, v3
	s_nop 1
	v_cndmask_b32_e32 v159, v174, v159, vcc
	v_sub_f32_e32 v3, v174, v159
	v_mul_f32_e32 v3, 0x3fb8aa3b, v3
	v_exp_f32_e32 v169, v3
	v_mul_f32_e32 v3, 0xbfb8aa3b, v159
	v_fmamk_f32 v124, v124, 0x3fb8aa3b, v3
	v_exp_f32_e32 v167, v124
	v_fmamk_f32 v125, v125, 0x3fb8aa3b, v3
	v_exp_f32_e32 v168, v125
	v_fmamk_f32 v125, v126, 0x3fb8aa3b, v3
	v_exp_f32_e32 v170, v125
	v_fmamk_f32 v125, v127, 0x3fb8aa3b, v3
	v_exp_f32_e32 v171, v125
	v_fmamk_f32 v125, v162, 0x3fb8aa3b, v3
	v_add_f32_e32 v124, 0, v167
	v_exp_f32_e32 v172, v125
	v_fmamk_f32 v125, v163, 0x3fb8aa3b, v3
	v_add_f32_e32 v124, v168, v124
	v_exp_f32_e32 v173, v125
	v_fmamk_f32 v125, v164, 0x3fb8aa3b, v3
	v_add_f32_e32 v124, v170, v124
	v_exp_f32_e32 v174, v125
	v_fmamk_f32 v125, v165, 0x3fb8aa3b, v3
	v_add_f32_e32 v124, v171, v124
	v_exp_f32_e32 v175, v125
	v_fmamk_f32 v125, v176, 0x3fb8aa3b, v3
	v_add_f32_e32 v124, v172, v124
	v_exp_f32_e32 v125, v125
	v_fmamk_f32 v126, v177, 0x3fb8aa3b, v3
	v_add_f32_e32 v124, v173, v124
	v_exp_f32_e32 v126, v126
	v_fmamk_f32 v127, v178, 0x3fb8aa3b, v3
	v_add_f32_e32 v124, v174, v124
	v_exp_f32_e32 v127, v127
	v_fmamk_f32 v162, v179, 0x3fb8aa3b, v3
	v_add_f32_e32 v124, v175, v124
	v_exp_f32_e32 v162, v162
	v_fmamk_f32 v163, v180, 0x3fb8aa3b, v3
	v_add_f32_e32 v124, v125, v124
	v_exp_f32_e32 v163, v163
	v_fmamk_f32 v164, v181, 0x3fb8aa3b, v3
	v_add_f32_e32 v124, v126, v124
	v_exp_f32_e32 v164, v164
	v_fmamk_f32 v165, v182, 0x3fb8aa3b, v3
	v_add_f32_e32 v124, v127, v124
	v_exp_f32_e32 v165, v165
	v_fmac_f32_e32 v3, 0x3fb8aa3b, v183
	v_add_f32_e32 v124, v162, v124
	v_exp_f32_e32 v166, v3
	v_add_f32_e32 v124, v163, v124
	v_add_f32_e32 v124, v164, v124
	v_add_f32_e32 v124, v165, v124
	v_add_f32_e32 v3, v166, v124
	v_mov_b32_e32 v124, v3
	s_nop 1
	v_permlane16_swap_b32 v124, v3
	v_cmp_neq_f32_e32 vcc, 1.0, v169
	s_waitcnt lgkmcnt(0)
	v_add_f32_e32 v3, v3, v124
	v_mov_b32_e32 v176, v3
	s_nop 1
	v_permlane32_swap_b32 v176, v3
	s_cbranch_vccz .LBB0_1312
	ds_bpermute_b32 v178, v146, v169
	ds_bpermute_b32 v180, v144, v169
	ds_bpermute_b32 v181, v145, v169
	ds_bpermute_b32 v179, v147, v169
	s_waitcnt lgkmcnt(1)
	v_pk_mul_f32 v[66:67], v[66:67], v[180:181]
	s_waitcnt lgkmcnt(0)
	v_pk_mul_f32 v[64:65], v[64:65], v[178:179]
	v_pk_mul_f32 v[58:59], v[58:59], v[180:181]
	v_pk_mul_f32 v[56:57], v[56:57], v[178:179]
	v_pk_mul_f32 v[50:51], v[50:51], v[180:181]
	v_pk_mul_f32 v[48:49], v[48:49], v[178:179]
	v_pk_mul_f32 v[42:43], v[42:43], v[180:181]
	v_pk_mul_f32 v[40:41], v[40:41], v[178:179]
	v_pk_mul_f32 v[34:35], v[34:35], v[180:181]
	v_pk_mul_f32 v[32:33], v[32:33], v[178:179]
	v_pk_mul_f32 v[26:27], v[26:27], v[180:181]
	v_pk_mul_f32 v[24:25], v[24:25], v[178:179]
	v_pk_mul_f32 v[18:19], v[18:19], v[180:181]
	v_pk_mul_f32 v[16:17], v[16:17], v[178:179]
	v_pk_mul_f32 v[14:15], v[14:15], v[180:181]
	v_pk_mul_f32 v[12:13], v[12:13], v[178:179]
.LBB0_1312:
	v_max3_f32 v124, v108, s76, v109
	v_max3_f32 v124, v124, v110, v111
	v_max3_f32 v124, v124, v112, v113
	v_max3_f32 v124, v124, v114, v115
	v_max3_f32 v124, v124, v116, v117
	v_max3_f32 v124, v124, v118, v119
	v_max3_f32 v124, v124, v120, v121
	v_max3_f32 v124, v124, v122, v123
	v_mov_b32_e32 v177, v124
	s_nop 1
	v_permlane16_swap_b32 v177, v124
	s_waitcnt lgkmcnt(0)
	v_max_f32_e32 v177, v177, v177
	v_max_f32_e32 v124, v124, v177
	v_mov_b32_e32 v177, v124
	s_nop 1
	v_permlane32_swap_b32 v177, v124
	s_waitcnt lgkmcnt(0)
	v_max3_f32 v124, v161, v124, v177
	v_sub_f32_e32 v177, v124, v161
	v_cmp_lt_f32_e32 vcc, 0x40b17218, v177
	s_nop 1
	v_cndmask_b32_e32 v124, v161, v124, vcc
	v_mul_f32_e32 v178, 0xbfb8aa3b, v124
	v_fmamk_f32 v108, v108, 0x3fb8aa3b, v178
	v_fmamk_f32 v109, v109, 0x3fb8aa3b, v178
	v_exp_f32_e32 v108, v108
	v_fmamk_f32 v110, v110, 0x3fb8aa3b, v178
	v_exp_f32_e32 v109, v109
	v_fmamk_f32 v111, v111, 0x3fb8aa3b, v178
	v_exp_f32_e32 v110, v110
	v_fmamk_f32 v112, v112, 0x3fb8aa3b, v178
	v_exp_f32_e32 v111, v111
	v_fmamk_f32 v113, v113, 0x3fb8aa3b, v178
	v_exp_f32_e32 v112, v112
	v_add_f32_e32 v177, 0, v108
	v_fmamk_f32 v114, v114, 0x3fb8aa3b, v178
	v_exp_f32_e32 v113, v113
	v_add_f32_e32 v177, v109, v177
	v_add_f32_e32 v177, v110, v177
	v_exp_f32_e32 v114, v114
	v_fmamk_f32 v115, v115, 0x3fb8aa3b, v178
	v_add_f32_e32 v179, v111, v177
	v_exp_f32_e32 v177, v115
	v_fmamk_f32 v116, v116, 0x3fb8aa3b, v178
	v_add_f32_e32 v115, v112, v179
	v_exp_f32_e32 v116, v116
	v_fmamk_f32 v117, v117, 0x3fb8aa3b, v178
	v_add_f32_e32 v115, v113, v115
	v_exp_f32_e32 v117, v117
	v_fmamk_f32 v118, v118, 0x3fb8aa3b, v178
	v_add_f32_e32 v115, v114, v115
	v_exp_f32_e32 v118, v118
	v_fmamk_f32 v119, v119, 0x3fb8aa3b, v178
	v_add_f32_e32 v115, v177, v115
	v_exp_f32_e32 v119, v119
	v_fmamk_f32 v120, v120, 0x3fb8aa3b, v178
	v_add_f32_e32 v115, v116, v115
	v_exp_f32_e32 v120, v120
	v_fmamk_f32 v121, v121, 0x3fb8aa3b, v178
	v_add_f32_e32 v115, v117, v115
	v_exp_f32_e32 v121, v121
	v_fmamk_f32 v122, v122, 0x3fb8aa3b, v178
	v_add_f32_e32 v115, v118, v115
	v_exp_f32_e32 v122, v122
	v_fmac_f32_e32 v178, 0x3fb8aa3b, v123
	v_add_f32_e32 v115, v119, v115
	v_exp_f32_e32 v123, v178
	v_add_f32_e32 v115, v120, v115
	v_add_f32_e32 v115, v121, v115
	v_add_f32_e32 v115, v122, v115
	v_add_f32_e32 v115, v123, v115
	v_mov_b32_e32 v178, v115
	s_nop 1
	v_permlane16_swap_b32 v178, v115
	v_sub_f32_e32 v161, v161, v124
	v_mul_f32_e32 v161, 0x3fb8aa3b, v161
	v_exp_f32_e32 v161, v161
	s_waitcnt lgkmcnt(0)
	v_add_f32_e32 v115, v115, v178
	v_mov_b32_e32 v178, v115
	s_nop 1
	v_permlane32_swap_b32 v178, v115
	v_cmp_neq_f32_e32 vcc, 1.0, v161
	s_cbranch_vccz .LBB0_1314
	ds_bpermute_b32 v180, v146, v161
	ds_bpermute_b32 v182, v144, v161
	ds_bpermute_b32 v183, v145, v161
	ds_bpermute_b32 v181, v147, v161
	s_waitcnt lgkmcnt(1)
	v_pk_mul_f32 v[62:63], v[62:63], v[182:183]
	s_waitcnt lgkmcnt(0)
	v_pk_mul_f32 v[60:61], v[60:61], v[180:181]
	v_pk_mul_f32 v[54:55], v[54:55], v[182:183]
	v_pk_mul_f32 v[52:53], v[52:53], v[180:181]
	v_pk_mul_f32 v[46:47], v[46:47], v[182:183]
	v_pk_mul_f32 v[44:45], v[44:45], v[180:181]
	v_pk_mul_f32 v[38:39], v[38:39], v[182:183]
	v_pk_mul_f32 v[36:37], v[36:37], v[180:181]
	v_pk_mul_f32 v[30:31], v[30:31], v[182:183]
	v_pk_mul_f32 v[28:29], v[28:29], v[180:181]
	v_pk_mul_f32 v[22:23], v[22:23], v[182:183]
	v_pk_mul_f32 v[20:21], v[20:21], v[180:181]
	v_pk_mul_f32 v[10:11], v[10:11], v[182:183]
	v_pk_mul_f32 v[8:9], v[8:9], v[180:181]
	v_pk_mul_f32 v[6:7], v[6:7], v[182:183]
	v_pk_mul_f32 v[4:5], v[4:5], v[180:181]

.LBB0_1316:
	s_barrier
	s_waitcnt vmcnt(5)
	ds_write_b128 v154, v[84:87]
	s_waitcnt vmcnt(4)
	ds_write_b128 v155, v[88:91]
	s_waitcnt vmcnt(3)
	ds_write_b128 v154, v[92:95] offset:9216
	s_waitcnt vmcnt(2)
	ds_write_b128 v155, v[96:99] offset:9216
	s_waitcnt vmcnt(1)
	ds_write_b128 v156, v[100:103] offset:9216
	s_waitcnt vmcnt(0)
	ds_write_b128 v157, v[104:107] offset:9216
	s_waitcnt lgkmcnt(0)
	s_barrier
	ds_read_b128 v[84:87], v2
	ds_read_b128 v[92:95], v2 offset:64
	s_waitcnt lgkmcnt(1)
	v_mfma_f32_16x16x32_bf16 v[88:91], v[84:87], v[72:75], 0
	ds_read_b128 v[100:103], v2 offset:2368
	ds_read_b128 v[116:119], v2 offset:4672
	v_mfma_f32_16x16x32_bf16 v[84:87], v[84:87], v[76:79], 0
	s_waitcnt lgkmcnt(2)
	v_mfma_f32_16x16x32_bf16 v[96:99], v[92:95], v[68:71], v[88:91]
	v_mfma_f32_16x16x32_bf16 v[92:95], v[92:95], v[80:83], v[84:87]
	s_nop 4
	ds_read_b128 v[84:87], v2 offset:2304
	s_waitcnt lgkmcnt(0)
	v_mfma_f32_16x16x32_bf16 v[88:91], v[84:87], v[72:75], 0
	v_mfma_f32_16x16x32_bf16 v[84:87], v[84:87], v[76:79], 0
	v_mfma_f32_16x16x32_bf16 v[104:107], v[100:103], v[68:71], v[88:91]
	v_mfma_f32_16x16x32_bf16 v[88:91], v[100:103], v[80:83], v[84:87]
	s_nop 5
	ds_read_b128 v[84:87], v2 offset:4608
	s_waitcnt lgkmcnt(0)
	v_mfma_f32_16x16x32_bf16 v[100:103], v[84:87], v[72:75], 0
	v_mfma_f32_16x16x32_bf16 v[84:87], v[84:87], v[76:79], 0
	v_mfma_f32_16x16x32_bf16 v[100:103], v[116:119], v[68:71], v[100:103]
	v_mfma_f32_16x16x32_bf16 v[84:87], v[116:119], v[80:83], v[84:87]
	ds_read_b128 v[116:119], v2 offset:6912
	s_waitcnt lgkmcnt(0)
	v_mfma_f32_16x16x32_bf16 v[72:75], v[116:119], v[72:75], 0
	v_mfma_f32_16x16x32_bf16 v[76:79], v[116:119], v[76:79], 0
	ds_read_b128 v[116:119], v2 offset:6976
	v_max3_f32 v2, v96, s76, v97
	v_max3_f32 v2, v2, v98, v99
	s_waitcnt lgkmcnt(0)
	v_mfma_f32_16x16x32_bf16 v[120:123], v[116:119], v[68:71], v[72:75]
	v_max3_f32 v2, v2, v104, v105
	v_max3_f32 v2, v2, v106, v107
	v_max3_f32 v2, v2, v100, v101
	v_max3_f32 v2, v2, v102, v103
	s_nop 3
	v_max3_f32 v2, v2, v120, v121
	v_max3_f32 v2, v2, v122, v123
	v_mov_b32_e32 v72, v2
	s_nop 1
	v_permlane16_swap_b32 v72, v2
	v_mfma_f32_16x16x32_bf16 v[68:71], v[116:119], v[80:83], v[76:79]
	s_waitcnt lgkmcnt(0)
	v_max_f32_e32 v72, v72, v72
	v_max_f32_e32 v2, v2, v72
	v_mov_b32_e32 v72, v2
	s_nop 1
	v_permlane32_swap_b32 v72, v2
	s_waitcnt lgkmcnt(0)
	v_max3_f32 v2, v159, v2, v72
	v_sub_f32_e32 v72, v2, v159
	v_cmp_lt_f32_e32 vcc, 0x40b17218, v72
	s_nop 1
	v_cndmask_b32_e32 v2, v159, v2, vcc
	v_sub_f32_e32 v72, v159, v2
	v_mul_f32_e32 v78, 0xbfb8aa3b, v2
	v_mul_f32_e32 v72, 0x3fb8aa3b, v72
	v_fmamk_f32 v2, v96, 0x3fb8aa3b, v78
	v_exp_f32_e32 v80, v72
	v_exp_f32_e32 v79, v2
	v_fmamk_f32 v72, v97, 0x3fb8aa3b, v78
	v_exp_f32_e32 v81, v72
	v_fmamk_f32 v72, v98, 0x3fb8aa3b, v78
	v_exp_f32_e32 v82, v72
	v_fmamk_f32 v72, v99, 0x3fb8aa3b, v78
	v_exp_f32_e32 v83, v72
	v_fmamk_f32 v72, v104, 0x3fb8aa3b, v78
	v_add_f32_e32 v2, 0, v79
	v_exp_f32_e32 v96, v72
	v_fmamk_f32 v72, v105, 0x3fb8aa3b, v78
	v_add_f32_e32 v2, v81, v2
	v_exp_f32_e32 v97, v72
	v_fmamk_f32 v72, v106, 0x3fb8aa3b, v78
	v_add_f32_e32 v2, v82, v2
	v_exp_f32_e32 v98, v72
	v_fmamk_f32 v72, v107, 0x3fb8aa3b, v78
	v_add_f32_e32 v2, v83, v2
	v_exp_f32_e32 v99, v72
	v_add_f32_e32 v2, v96, v2
	v_add_f32_e32 v2, v97, v2
	v_add_f32_e32 v2, v98, v2
	v_add_f32_e32 v72, v99, v2
	v_fmamk_f32 v2, v100, 0x3fb8aa3b, v78
	v_exp_f32_e32 v2, v2
	v_cmp_neq_f32_e32 vcc, 1.0, v80
	v_add_f32_e32 v73, v2, v72
	v_fmamk_f32 v72, v101, 0x3fb8aa3b, v78
	v_exp_f32_e32 v72, v72
	s_nop 0
	v_add_f32_e32 v74, v72, v73
	v_fmamk_f32 v73, v102, 0x3fb8aa3b, v78
	v_exp_f32_e32 v73, v73
	s_nop 0
	v_add_f32_e32 v75, v73, v74
	v_fmamk_f32 v74, v103, 0x3fb8aa3b, v78
	v_exp_f32_e32 v74, v74
	s_nop 0
	v_add_f32_e32 v76, v74, v75
	v_fmamk_f32 v75, v120, 0x3fb8aa3b, v78
	v_exp_f32_e32 v75, v75
	s_nop 0
	v_add_f32_e32 v77, v75, v76
	v_fmamk_f32 v76, v121, 0x3fb8aa3b, v78
	v_exp_f32_e32 v76, v76
	s_nop 0
	v_add_f32_e32 v100, v76, v77
	v_fmamk_f32 v77, v122, 0x3fb8aa3b, v78
	v_exp_f32_e32 v77, v77
	v_fmac_f32_e32 v78, 0x3fb8aa3b, v123
	v_exp_f32_e32 v78, v78
	v_add_f32_e32 v100, v77, v100
	v_add_f32_e32 v100, v78, v100
	v_mov_b32_e32 v101, v100
	s_nop 1
	v_permlane16_swap_b32 v101, v100
	s_waitcnt lgkmcnt(0)
	v_add_f32_e32 v100, v100, v101
	v_mov_b32_e32 v101, v100
	s_nop 1
	v_permlane32_swap_b32 v101, v100
	s_cbranch_vccz .LBB0_1318
	ds_bpermute_b32 v102, v146, v80
	ds_bpermute_b32 v104, v144, v80
	ds_bpermute_b32 v105, v145, v80
	ds_bpermute_b32 v103, v147, v80
	s_waitcnt lgkmcnt(1)
	v_pk_mul_f32 v[66:67], v[66:67], v[104:105]
	s_waitcnt lgkmcnt(0)
	v_pk_mul_f32 v[64:65], v[64:65], v[102:103]
	v_pk_mul_f32 v[58:59], v[58:59], v[104:105]
	v_pk_mul_f32 v[56:57], v[56:57], v[102:103]
	v_pk_mul_f32 v[50:51], v[50:51], v[104:105]
	v_pk_mul_f32 v[48:49], v[48:49], v[102:103]
	v_pk_mul_f32 v[42:43], v[42:43], v[104:105]
	v_pk_mul_f32 v[40:41], v[40:41], v[102:103]
	v_pk_mul_f32 v[34:35], v[34:35], v[104:105]
	v_pk_mul_f32 v[32:33], v[32:33], v[102:103]
	v_pk_mul_f32 v[26:27], v[26:27], v[104:105]
	v_pk_mul_f32 v[24:25], v[24:25], v[102:103]
	v_pk_mul_f32 v[18:19], v[18:19], v[104:105]
	v_pk_mul_f32 v[16:17], v[16:17], v[102:103]
	v_pk_mul_f32 v[14:15], v[14:15], v[104:105]
	v_pk_mul_f32 v[12:13], v[12:13], v[102:103]
.LBB0_1318:
	v_max3_f32 v102, v92, s76, v93
	v_max3_f32 v102, v102, v94, v95
	v_max3_f32 v102, v102, v88, v89
	v_max3_f32 v102, v102, v90, v91
	v_max3_f32 v102, v102, v84, v85
	v_max3_f32 v102, v102, v86, v87
	v_max3_f32 v102, v102, v68, v69
	v_max3_f32 v102, v102, v70, v71
	v_mov_b32_e32 v103, v102
	s_nop 1
	v_permlane16_swap_b32 v103, v102
	s_waitcnt lgkmcnt(0)
	v_max_f32_e32 v103, v103, v103
	v_max_f32_e32 v102, v102, v103
	v_mov_b32_e32 v103, v102
	s_nop 1
	v_permlane32_swap_b32 v103, v102
	s_waitcnt lgkmcnt(0)
	v_max3_f32 v103, v124, v102, v103
	v_sub_f32_e32 v102, v103, v124
	v_cmp_lt_f32_e32 vcc, 0x40b17218, v102
	s_nop 1
	v_cndmask_b32_e32 v103, v124, v103, vcc
	v_mul_f32_e32 v104, 0xbfb8aa3b, v103
	v_fmamk_f32 v92, v92, 0x3fb8aa3b, v104
	v_exp_f32_e32 v92, v92
	v_fmamk_f32 v93, v93, 0x3fb8aa3b, v104
	v_exp_f32_e32 v93, v93
	v_fmamk_f32 v94, v94, 0x3fb8aa3b, v104
	v_exp_f32_e32 v94, v94
	v_fmamk_f32 v95, v95, 0x3fb8aa3b, v104
	v_exp_f32_e32 v95, v95
	v_sub_f32_e32 v102, v124, v103
	v_add_f32_e32 v103, 0, v92
	v_add_f32_e32 v103, v93, v103
	v_add_f32_e32 v103, v94, v103
	v_fmamk_f32 v88, v88, 0x3fb8aa3b, v104
	v_add_f32_e32 v105, v95, v103
	v_exp_f32_e32 v103, v88
	v_fmamk_f32 v89, v89, 0x3fb8aa3b, v104
	v_exp_f32_e32 v89, v89
	v_fmamk_f32 v90, v90, 0x3fb8aa3b, v104
	v_exp_f32_e32 v90, v90
	v_fmamk_f32 v91, v91, 0x3fb8aa3b, v104
	v_exp_f32_e32 v91, v91
	v_add_f32_e32 v88, v103, v105
	v_add_f32_e32 v88, v89, v88
	v_add_f32_e32 v88, v90, v88
	v_fmamk_f32 v84, v84, 0x3fb8aa3b, v104
	v_add_f32_e32 v105, v91, v88
	v_exp_f32_e32 v88, v84
	v_fmamk_f32 v85, v85, 0x3fb8aa3b, v104
	v_exp_f32_e32 v85, v85
	v_fmamk_f32 v86, v86, 0x3fb8aa3b, v104
	v_exp_f32_e32 v86, v86
	v_fmamk_f32 v87, v87, 0x3fb8aa3b, v104
	v_exp_f32_e32 v87, v87
	v_fmamk_f32 v68, v68, 0x3fb8aa3b, v104
	v_add_f32_e32 v84, v88, v105
	v_exp_f32_e32 v68, v68
	v_fmamk_f32 v69, v69, 0x3fb8aa3b, v104
	v_add_f32_e32 v84, v85, v84
	v_exp_f32_e32 v69, v69
	v_fmamk_f32 v70, v70, 0x3fb8aa3b, v104
	v_add_f32_e32 v84, v86, v84
	v_exp_f32_e32 v70, v70
	v_fmac_f32_e32 v104, 0x3fb8aa3b, v71
	v_add_f32_e32 v84, v87, v84
	v_exp_f32_e32 v71, v104
	v_add_f32_e32 v84, v68, v84
	v_add_f32_e32 v84, v69, v84
	v_add_f32_e32 v84, v70, v84
	v_add_f32_e32 v84, v71, v84
	v_mov_b32_e32 v104, v84
	s_nop 1
	v_permlane16_swap_b32 v104, v84
	v_mul_f32_e32 v102, 0x3fb8aa3b, v102
	v_exp_f32_e32 v102, v102
	s_waitcnt lgkmcnt(0)
	v_add_f32_e32 v84, v84, v104
	v_mov_b32_e32 v104, v84
	s_nop 1
	v_permlane32_swap_b32 v104, v84
	v_cmp_neq_f32_e32 vcc, 1.0, v102
	s_cbranch_vccz .LBB0_1320
	ds_bpermute_b32 v106, v146, v102
	ds_bpermute_b32 v116, v144, v102
	ds_bpermute_b32 v117, v145, v102
	ds_bpermute_b32 v107, v147, v102
	s_waitcnt lgkmcnt(1)
	v_pk_mul_f32 v[62:63], v[62:63], v[116:117]
	s_waitcnt lgkmcnt(0)
	v_pk_mul_f32 v[60:61], v[60:61], v[106:107]
	v_pk_mul_f32 v[54:55], v[54:55], v[116:117]
	v_pk_mul_f32 v[52:53], v[52:53], v[106:107]
	v_pk_mul_f32 v[46:47], v[46:47], v[116:117]
	v_pk_mul_f32 v[44:45], v[44:45], v[106:107]
	v_pk_mul_f32 v[38:39], v[38:39], v[116:117]
	v_pk_mul_f32 v[36:37], v[36:37], v[106:107]
	v_pk_mul_f32 v[30:31], v[30:31], v[116:117]
	v_pk_mul_f32 v[28:29], v[28:29], v[106:107]
	v_pk_mul_f32 v[22:23], v[22:23], v[116:117]
	v_pk_mul_f32 v[20:21], v[20:21], v[106:107]
	v_pk_mul_f32 v[10:11], v[10:11], v[116:117]
	v_pk_mul_f32 v[8:9], v[8:9], v[106:107]
	v_pk_mul_f32 v[6:7], v[6:7], v[116:117]
	v_pk_mul_f32 v[4:5], v[4:5], v[106:107]
